# 7 grid barriers (after P2,P8,P10,P12,P14,P15,P16) replaced by 32-WG XCD-group-local barriers without L2 writeback (runtime placement check, full-barrier fallback)
# speedup vs baseline: 1.0044x; 1.0044x over previous
_Z10fwd_kernel4Args:
	v_mov_b32_e32 v243, 0
	v_writelane_b32 v242, 0, 63
	s_load_dword s3, s[0:1], 0xd8
	s_load_dwordx4 s[76:79], s[0:1], 0xc0
	s_load_dwordx2 s[60:61], s[0:1], 0xd0
	v_and_b32_e32 v185, 0x3ff, v0
	s_add_u32 s6, s0, 0xd0
	v_readfirstlane_b32 s74, v185
	s_addc_u32 s7, s1, 0
	v_cmp_gt_u32_e32 vcc, 16, v185
	s_waitcnt lgkmcnt(0)
	v_writelane_b32 v242, s3, 0
	s_and_saveexec_b64 s[4:5], vcc
	v_lshl_add_u32 v1, v185, 2, 0
	v_add_u32_e32 v1, 0x21000, v1
	v_mov_b32_e32 v2, 0
	ds_write_b32 v1, v2
	s_or_b64 exec, exec, s[4:5]
	s_waitcnt lgkmcnt(0)
	s_barrier
	s_getreg_b32 s3, hwreg(HW_REG_XCC_ID, 0, 4)
	s_and_b32 s84, s3, 15
	v_cmp_eq_u32_e64 s[8:9], 0, v185
	s_mov_b64 s[4:5], exec
	s_nop 0
	v_writelane_b32 v242, s8, 1
	s_nop 1
	v_writelane_b32 v242, s9, 2
	s_and_b64 s[8:9], s[4:5], s[8:9]
	s_mov_b64 exec, s[8:9]
	s_cbranch_execz .LBB0_5
	s_mov_b64 s[8:9], exec
	v_mbcnt_lo_u32_b32 v1, s8, 0
	v_mbcnt_hi_u32_b32 v1, s9, v1
	v_cmp_eq_u32_e32 vcc, 0, v1
	s_and_b64 s[10:11], exec, vcc
	s_mov_b64 exec, s[10:11]
	s_cbranch_execz .LBB0_5
	s_and_b32 s3, s2, 7
	s_cmp_eq_u32 s3, s84
	s_cbranch_scc1 .Llb_regok
	v_mov_b32_e32 v1, 0x3000
	v_mov_b32_e32 v2, 1
	global_atomic_add v1, v2, s[76:77] offset:2048 sc1
.Llb_regok:
	s_lshl_b32 s3, s84, 8
	s_bcnt1_i32_b64 s8, s[8:9]
	v_mov_b32_e32 v1, s3
	v_mov_b32_e32 v2, s8
	global_atomic_add v1, v2, s[76:77] offset:1024

.LBB0_100:
	s_or_b64 exec, exec, s[0:1]
	s_waitcnt lgkmcnt(0)
	s_barrier
	v_readlane_b32 s12, v242, 63
	s_add_u32 s12, s12, 1
	v_writelane_b32 v242, s12, 63
	v_mov_b32_e32 v0, 0x3000
	global_load_dword v0, v0, s[76:77] offset:2048 sc1
	v_readlane_b32 s13, v242, 0
	s_waitcnt vmcnt(0)
	v_readfirstlane_b32 s12, v0
	s_cmp_eq_u32 s12, 0
	s_cselect_b32 s12, 1, 0
	s_cmp_eq_u32 s13, 0x100
	s_cselect_b32 s12, s12, 0
	v_writelane_b32 v243, s12, 0

.LBB0_470:
	s_cmp_gt_i32 s79, 3
	s_cselect_b64 s[0:1], -1, 0
	s_and_b64 s[4:5], s[10:11], s[0:1]
	v_readlane_b32 s64, v242, 58
	s_andn2_b64 vcc, exec, s[4:5]
	v_readlane_b32 s65, v242, 59
	s_cbranch_vccnz .LBB0_524
	s_waitcnt vmcnt(0) lgkmcnt(0)
	s_barrier
	v_readlane_b32 s12, v243, 0
	s_cmp_eq_u32 s12, 0
	s_cbranch_scc1 .Lfb_2
	v_readlane_b32 s21, v243, 1
	s_add_u32 s21, s21, 1
	v_writelane_b32 v243, s21, 1
	v_readlane_b32 s12, v242, 1
	v_readlane_b32 s13, v242, 2
	s_mov_b64 s[14:15], exec
	s_and_b64 s[12:13], s[14:15], s[12:13]
	s_mov_b64 exec, s[12:13]
	s_cbranch_execz .Llb_done_2
	s_and_b32 s16, s2, 7
	s_lshl_b32 s16, s16, 6
	s_add_u32 s16, s76, s16
	s_addc_u32 s17, s77, 0
	v_mov_b32_e32 v1, 0x3000
	v_mov_b32_e32 v4, 1
	global_atomic_add v1, v4, s[16:17] offset:2112
	buffer_inv sc1
	s_lshl_b32 s23, s21, 5
.Llb_spin_2:
	global_load_dword v6, v1, s[16:17] offset:2112 sc1
	s_waitcnt vmcnt(0)
	v_readfirstlane_b32 s24, v6
	s_sub_u32 s24, s24, s23
	s_cmp_ge_i32 s24, 0
	s_cbranch_scc1 .Llb_done_2
	s_sleep 1
	s_branch .Llb_spin_2
.Llb_done_2:
	s_mov_b64 exec, s[14:15]
	s_barrier
	s_branch .Llb_after_2
.Lfb_2:
	v_readlane_b32 s21, v242, 63
	s_add_u32 s21, s21, 1
	v_readlane_b32 s12, v242, 1
	v_readlane_b32 s13, v242, 2
	s_mov_b64 s[14:15], exec
	s_and_b64 s[12:13], s[14:15], s[12:13]
	s_mov_b64 exec, s[12:13]
	s_cbranch_execz .Lxb_done_2
	v_mov_b32_e32 v0, 0x21020
	ds_read2_b32 v[2:3], v0 offset1:1
	s_lshl_b32 s16, s84, 8
	s_add_u32 s16, s76, s16
	s_addc_u32 s17, s77, 0
	v_mov_b32_e32 v1, 0x1000
	v_mov_b32_e32 v4, 1
	global_atomic_add v5, v1, v4, s[16:17] offset:1024 sc0
	buffer_inv sc1
	s_waitcnt vmcnt(0) lgkmcnt(0)
	v_readfirstlane_b32 s18, v5
	v_readfirstlane_b32 s19, v2
	v_readfirstlane_b32 s20, v3
	v_mov_b32_e32 v1, 0x3000
	s_mul_i32 s22, s19, s21
	s_mul_i32 s23, s20, s21
	s_add_u32 s18, s18, 1
	s_cmp_lg_u32 s18, s22
	s_cbranch_scc1 .Lxb_spin_2
	buffer_wbl2 sc1
	s_waitcnt vmcnt(0)
	global_atomic_add v1, v4, s[76:77] offset:1024

.Llb_after_2:
.LBB0_524:
	s_cmp_lt_i32 s78, 4
	s_cselect_b64 s[24:25], -1, 0
	s_and_b64 s[0:1], s[24:25], s[0:1]
	s_andn2_b64 vcc, exec, s[0:1]
	s_cbranch_vccnz .LBB0_759
	s_cmpk_gt_i32 s2, 0x1ff
	s_cselect_b64 s[0:1], -1, 0
	v_readfirstlane_b32 s8, v185
	s_and_b64 vcc, exec, s[0:1]
	s_cbranch_vccnz .LBB0_531
	s_ashr_i32 s3, s2, 31
	s_lshr_b32 s3, s3, 29
	s_add_i32 s3, s2, s3
	s_and_b32 s4, s3, -8
	s_sub_i32 s6, s2, s4
	s_cmp_gt_i32 s6, -1
	s_cbranch_scc0 .LBB0_528
	s_lshl_b32 s7, s6, 6
	s_cbranch_execz .LBB0_529
	s_branch .LBB0_530

.LBB0_1051:
	s_cmp_gt_i32 s79, 9
	s_cselect_b64 s[4:5], -1, 0
	s_and_b64 s[0:1], s[0:1], s[4:5]
	s_andn2_b64 vcc, exec, s[0:1]
	s_cbranch_vccnz .LBB0_1105
	s_waitcnt vmcnt(0) lgkmcnt(0)
	s_barrier
	v_readlane_b32 s12, v243, 0
	s_cmp_eq_u32 s12, 0
	s_cbranch_scc1 .Lfb_6
	v_readlane_b32 s21, v243, 1
	s_add_u32 s21, s21, 1
	v_writelane_b32 v243, s21, 1
	v_readlane_b32 s12, v242, 1
	v_readlane_b32 s13, v242, 2
	s_mov_b64 s[14:15], exec
	s_and_b64 s[12:13], s[14:15], s[12:13]
	s_mov_b64 exec, s[12:13]
	s_cbranch_execz .Llb_done_6
	s_and_b32 s16, s2, 7
	s_lshl_b32 s16, s16, 6
	s_add_u32 s16, s76, s16
	s_addc_u32 s17, s77, 0
	v_mov_b32_e32 v1, 0x3000
	v_mov_b32_e32 v4, 1
	global_atomic_add v1, v4, s[16:17] offset:2112
	buffer_inv sc1
	s_lshl_b32 s23, s21, 5

.Llb_after_6:
.LBB0_1105:
	s_cmp_lt_i32 s78, 10
	s_cselect_b64 s[0:1], -1, 0
	s_and_b64 s[4:5], s[0:1], s[4:5]
	s_andn2_b64 vcc, exec, s[4:5]
	s_cbranch_vccnz .LBB0_1246
	s_add_u32 s6, s76, 0x1480000
	s_addc_u32 s7, s77, 0
	s_cmpk_gt_i32 s2, 0x57f
	v_readfirstlane_b32 s5, v185
	s_cbranch_scc1 .LBB0_1122
	v_lshrrev_b32_e32 v0, 5, v185
	v_lshrrev_b32_e32 v2, 1, v185
	v_and_b32_e32 v0, 4, v0
	s_waitcnt lgkmcnt(0)
	v_bfe_u32 v1, v185, 2, 2
	v_and_b32_e32 v11, 24, v2
	v_or3_b32 v0, v0, v1, v11
	v_lshlrev_b32_e32 v1, 4, v185
	v_add_u32_e32 v8, 0x2000, v1
	v_lshrrev_b32_e32 v2, 7, v8
	s_movk_i32 s4, 0xe0
	v_and_b32_e32 v4, 32, v185
	v_and_or_b32 v3, v2, s4, v0
	v_bitop3_b32 v9, v1, v4, 48 bitop3:0x6c
	v_and_b32_e32 v10, 64, v185
	v_bfe_u32 v12, v185, 2, 4
	s_movk_i32 s4, 0xf0
	v_or_b32_e32 v1, v9, v10
	v_and_or_b32 v2, v2, s4, v12
	v_lshl_or_b32 v130, v2, 11, v1
	v_lshrrev_b32_e32 v2, 3, v185
	s_movk_i32 s4, 0x60
	v_and_or_b32 v0, v2, s4, v0
	s_movk_i32 s4, 0x70
	s_ashr_i32 s14, s2, 31
	v_lshl_or_b32 v132, v0, 11, v1
	v_and_or_b32 v0, v2, s4, v12
	s_lshr_b32 s4, s14, 29
	s_add_i32 s4, s2, s4
	s_lshr_b32 s12, s5, 6
	s_ashr_i32 s8, s4, 3
	s_and_b32 s4, s4, -8
	s_lshr_b32 s23, s5, 8
	s_lshl_b32 s3, s12, 10
	s_sub_i32 s4, s2, s4
	s_cmp_lt_i32 s4, 0
	s_movk_i32 s15, 0xb1
	s_cselect_b32 s9, s15, 0xb0
	s_mul_i32 s4, s4, s9
	s_add_i32 s4, s4, s8
	s_mul_hi_i32 s8, s4, 0x2e8ba2e9
	s_lshr_b32 s9, s8, 31
	s_ashr_i32 s8, s8, 4
	s_add_i32 s8, s8, s9
	s_lshl_b32 s9, s8, 2
	s_mulk_i32 s8, 0x58
	s_sub_i32 s8, s4, s8
	s_bfe_i32 s4, s8, 0x80000
	s_bfe_u32 s4, s4, 0x2000d
	s_add_i32 s10, s8, s4
	s_bfe_i32 s4, s10, 0x80000
	s_and_b32 s10, s10, 0xfc
	s_sub_i32 s8, s8, s10
	s_sext_i32_i16 s4, s4
	s_sext_i32_i8 s8, s8
	s_lshr_b32 s4, s4, 2
	s_add_i32 s36, s9, s8
	s_ashr_i32 s37, s36, 31
	s_bfe_i64 s[10:11], s[4:5], 0x100000
	s_lshl_b64 s[8:9], s[36:37], 19
	s_lshl_b64 s[10:11], s[10:11], 19
	s_add_u32 s40, s6, s10
	s_addc_u32 s41, s7, s11
	s_add_i32 s16, s3, 0
	s_add_i32 m0, s16, 0x10000
	v_lshl_or_b32 v128, v3, 11, v1
	global_load_lds_dwordx4 v132, s[40:41]
	s_add_i32 m0, s16, 0x12000
	s_add_u32 s10, s40, 0x40000
	global_load_lds_dwordx4 v128, s[40:41]
	s_addc_u32 s11, s41, 0
	s_add_i32 m0, s16, 0x14000
	v_lshl_or_b32 v134, v0, 11, v1
	global_load_lds_dwordx4 v132, s[10:11]
	s_add_i32 m0, s16, 0x16000
	s_add_u32 s38, s82, s8
	s_addc_u32 s39, s83, s9
	s_add_i32 s17, s16, 0x2000
	global_load_lds_dwordx4 v128, s[10:11]
	s_mov_b32 m0, s16
	s_add_u32 s8, s38, 0x40000
	global_load_lds_dwordx4 v134, s[38:39]
	s_mov_b32 m0, s17
	s_addc_u32 s9, s39, 0
	s_add_i32 s18, s16, 0x4000
	global_load_lds_dwordx4 v130, s[38:39]
	s_mov_b32 m0, s18
	s_add_i32 s19, s16, 0x6000
	global_load_lds_dwordx4 v134, s[8:9]
	s_mov_b32 m0, s19
	v_mov_b32_e32 v133, 0
	global_load_lds_dwordx4 v130, s[8:9]
	v_mov_b32_e32 v129, v133
	v_mov_b32_e32 v135, v133
	v_mov_b32_e32 v131, v133
	s_cmp_eq_u32 s23, 1
	s_mov_b32 s20, 0
	v_lshl_add_u64 v[6:7], s[40:41], 0, v[132:133]
	v_lshl_add_u64 v[4:5], s[40:41], 0, v[128:129]
	v_lshl_add_u64 v[0:1], s[38:39], 0, v[134:135]
	s_cselect_b64 s[8:9], -1, 0
	s_cmp_lg_u32 s23, 1
	v_lshl_add_u64 v[2:3], s[38:39], 0, v[130:131]
	s_cbranch_scc1 .LBB0_1109
	s_barrier

.LBB0_1349:
	s_cmp_gt_i32 s79, 11
	s_cselect_b64 s[4:5], -1, 0
	s_and_b64 s[0:1], s[10:11], s[4:5]
	s_andn2_b64 vcc, exec, s[0:1]
	s_cbranch_vccnz .LBB0_1403
	s_waitcnt vmcnt(0) lgkmcnt(0)
	s_barrier
	v_readlane_b32 s12, v243, 0
	s_cmp_eq_u32 s12, 0
	s_cbranch_scc1 .Lfb_8
	v_readlane_b32 s21, v243, 1
	s_add_u32 s21, s21, 1
	v_writelane_b32 v243, s21, 1
	v_readlane_b32 s12, v242, 1
	v_readlane_b32 s13, v242, 2
	s_mov_b64 s[14:15], exec
	s_and_b64 s[12:13], s[14:15], s[12:13]
	s_mov_b64 exec, s[12:13]
	s_cbranch_execz .Llb_done_8
	s_and_b32 s16, s2, 7
	s_lshl_b32 s16, s16, 6
	s_add_u32 s16, s76, s16
	s_addc_u32 s17, s77, 0
	v_mov_b32_e32 v1, 0x3000
	v_mov_b32_e32 v4, 1
	global_atomic_add v1, v4, s[16:17] offset:2112
	buffer_inv sc1
	s_lshl_b32 s23, s21, 5

.Llb_after_8:
.LBB0_1403:
	s_cmp_lt_i32 s78, 12
	s_cselect_b64 s[0:1], -1, 0
	s_and_b64 s[4:5], s[0:1], s[4:5]
	s_andn2_b64 vcc, exec, s[4:5]
	s_cbranch_vccnz .LBB0_1552
	s_add_u32 s6, s76, 0x2500000
	v_readlane_b32 s3, v242, 56
	s_addc_u32 s7, s77, 0
	s_mul_hi_u32 s3, s3, 0x780
	s_cmpk_gt_i32 s2, 0x77f
	v_readfirstlane_b32 s5, v185
	s_cbranch_scc1 .LBB0_1428
	v_lshrrev_b32_e32 v0, 5, v185
	v_lshrrev_b32_e32 v2, 1, v185
	v_and_b32_e32 v0, 4, v0
	s_waitcnt lgkmcnt(0)
	v_bfe_u32 v1, v185, 2, 2
	v_and_b32_e32 v2, 24, v2
	v_or3_b32 v0, v0, v1, v2
	v_lshlrev_b32_e32 v1, 4, v185
	v_add_u32_e32 v8, 0x2000, v1
	v_lshrrev_b32_e32 v2, 7, v8
	s_movk_i32 s4, 0xe0
	v_and_b32_e32 v4, 32, v185
	v_and_or_b32 v3, v2, s4, v0
	v_bitop3_b32 v9, v1, v4, 48 bitop3:0x6c
	v_and_b32_e32 v10, 64, v185
	v_bfe_u32 v11, v185, 2, 4
	s_movk_i32 s4, 0xf0
	v_or_b32_e32 v1, v9, v10
	v_and_or_b32 v2, v2, s4, v11
	v_lshl_or_b32 v138, v2, 11, v1
	v_lshrrev_b32_e32 v2, 3, v185
	s_movk_i32 s4, 0x60
	v_and_or_b32 v0, v2, s4, v0
	s_movk_i32 s4, 0x70
	s_ashr_i32 s61, s2, 31
	v_lshl_or_b32 v140, v0, 11, v1
	v_and_or_b32 v0, v2, s4, v11
	s_lshr_b32 s4, s61, 29
	s_add_i32 s4, s2, s4
	s_lshr_b32 s12, s5, 6
	s_ashr_i32 s8, s4, 3
	s_and_b32 s4, s4, -8
	s_lshr_b32 s14, s5, 8
	s_lshl_b32 s60, s12, 10
	s_sub_i32 s4, s2, s4
	s_cmp_lt_i32 s4, 0
	s_movk_i32 s62, 0xf1
	s_cselect_b32 s9, s62, 0xf0
	s_mul_i32 s4, s4, s9
	s_add_i32 s4, s4, s8
	s_mul_hi_i32 s8, s4, 0x88888889
	s_add_i32 s8, s8, s4
	s_lshr_b32 s9, s8, 31
	s_ashr_i32 s8, s8, 6
	s_add_i32 s8, s8, s9
	s_lshl_b32 s9, s8, 2
	s_mulk_i32 s8, 0x78
	s_sub_i32 s8, s4, s8
	s_bfe_i32 s4, s8, 0x80000
	s_bfe_u32 s4, s4, 0x2000d
	s_add_i32 s10, s8, s4
	s_bfe_i32 s4, s10, 0x80000
	s_and_b32 s10, s10, 0xfc
	s_sub_i32 s8, s8, s10
	s_sext_i32_i16 s4, s4
	s_sext_i32_i8 s8, s8
	s_lshr_b32 s4, s4, 2
	s_add_i32 s36, s9, s8
	s_ashr_i32 s37, s36, 31
	s_bfe_i64 s[10:11], s[4:5], 0x100000
	s_lshl_b64 s[8:9], s[36:37], 19
	s_lshl_b64 s[10:11], s[10:11], 19
	s_add_u32 s40, s6, s10
	s_addc_u32 s41, s7, s11
	s_add_i32 s37, s60, 0
	s_add_i32 m0, s37, 0x10000
	v_lshl_or_b32 v136, v3, 11, v1
	global_load_lds_dwordx4 v140, s[40:41]
	s_add_i32 m0, s37, 0x12000
	s_add_u32 s10, s40, 0x40000
	global_load_lds_dwordx4 v136, s[40:41]
	s_addc_u32 s11, s41, 0
	s_add_i32 m0, s37, 0x14000
	v_lshl_or_b32 v142, v0, 11, v1
	global_load_lds_dwordx4 v140, s[10:11]
	s_add_i32 m0, s37, 0x16000
	s_add_u32 s38, s82, s8
	s_addc_u32 s39, s83, s9
	s_add_i32 s63, s37, 0x2000
	global_load_lds_dwordx4 v136, s[10:11]
	s_mov_b32 m0, s37
	s_add_u32 s8, s38, 0x40000
	global_load_lds_dwordx4 v142, s[38:39]
	s_mov_b32 m0, s63
	s_addc_u32 s9, s39, 0
	s_add_i32 s64, s37, 0x4000
	global_load_lds_dwordx4 v138, s[38:39]
	s_mov_b32 m0, s64
	s_add_i32 s65, s37, 0x6000
	global_load_lds_dwordx4 v142, s[8:9]
	s_mov_b32 m0, s65
	v_mov_b32_e32 v145, 0
	global_load_lds_dwordx4 v138, s[8:9]
	v_mov_b32_e32 v141, v145
	v_mov_b32_e32 v137, v145
	v_mov_b32_e32 v143, v145
	v_mov_b32_e32 v139, v145
	s_cmp_eq_u32 s14, 1
	s_mov_b32 s66, 0
	v_lshl_add_u64 v[6:7], s[40:41], 0, v[140:141]
	v_lshl_add_u64 v[2:3], s[40:41], 0, v[136:137]
	v_lshl_add_u64 v[0:1], s[38:39], 0, v[142:143]
	s_cselect_b64 s[8:9], -1, 0
	s_cmp_lg_u32 s14, 1
	v_lshl_add_u64 v[4:5], s[38:39], 0, v[138:139]
	s_cbranch_scc1 .LBB0_1407
	s_barrier

.LBB0_1655:
	s_cmp_gt_i32 s79, 13
	s_cselect_b64 s[4:5], -1, 0
	s_and_b64 s[0:1], s[10:11], s[4:5]
	s_andn2_b64 vcc, exec, s[0:1]
	s_cbranch_vccnz .LBB0_1709
	s_waitcnt vmcnt(0) lgkmcnt(0)
	s_barrier
	v_readlane_b32 s12, v243, 0
	s_cmp_eq_u32 s12, 0
	s_cbranch_scc1 .Lfb_10
	v_readlane_b32 s21, v243, 1
	s_add_u32 s21, s21, 1
	v_writelane_b32 v243, s21, 1
	v_readlane_b32 s12, v242, 1
	v_readlane_b32 s13, v242, 2
	s_mov_b64 s[14:15], exec
	s_and_b64 s[12:13], s[14:15], s[12:13]
	s_mov_b64 exec, s[12:13]
	s_cbranch_execz .Llb_done_10
	s_and_b32 s16, s2, 7
	s_lshl_b32 s16, s16, 6
	s_add_u32 s16, s76, s16
	s_addc_u32 s17, s77, 0
	v_mov_b32_e32 v1, 0x3000
	v_mov_b32_e32 v4, 1
	global_atomic_add v1, v4, s[16:17] offset:2112
	buffer_inv sc1
	s_lshl_b32 s23, s21, 5

.Llb_after_10:
.LBB0_1709:
	s_cmp_lt_i32 s78, 14
	s_cselect_b64 s[0:1], -1, 0
	s_and_b64 s[4:5], s[0:1], s[4:5]
	s_andn2_b64 vcc, exec, s[4:5]
	s_cbranch_vccnz .LBB0_1734
	s_cmpk_gt_i32 s2, 0xff
	v_readfirstlane_b32 s12, v185
	s_cbranch_scc1 .LBB0_1734
	s_ashr_i32 s3, s2, 31
	s_lshr_b32 s4, s3, 29
	s_add_i32 s7, s2, s4
	s_and_b32 s4, s7, -8
	s_sub_i32 s8, s2, s4
	s_cmp_gt_i32 s8, -1
	s_cbranch_scc0 .LBB0_1713
	s_lshl_b32 s6, s8, 5
	s_cbranch_execz .LBB0_1714
	s_branch .LBB0_1715

.LBB0_1812:
	s_cmp_gt_i32 s79, 15
	s_cselect_b64 s[4:5], -1, 0
	s_and_b64 s[0:1], s[0:1], s[4:5]
	s_andn2_b64 vcc, exec, s[0:1]
	s_cbranch_vccnz .LBB0_1866
	s_waitcnt vmcnt(0) lgkmcnt(0)
	s_barrier
	v_readlane_b32 s12, v243, 0
	s_cmp_eq_u32 s12, 0
	s_cbranch_scc1 .Lfb_12
	v_readlane_b32 s21, v243, 1
	s_add_u32 s21, s21, 1
	v_writelane_b32 v243, s21, 1
	v_readlane_b32 s12, v242, 1
	v_readlane_b32 s13, v242, 2
	s_mov_b64 s[14:15], exec
	s_and_b64 s[12:13], s[14:15], s[12:13]
	s_mov_b64 exec, s[12:13]
	s_cbranch_execz .Llb_done_12
	s_and_b32 s16, s2, 7
	s_lshl_b32 s16, s16, 6
	s_add_u32 s16, s76, s16
	s_addc_u32 s17, s77, 0
	v_mov_b32_e32 v1, 0x3000
	v_mov_b32_e32 v4, 1
	global_atomic_add v1, v4, s[16:17] offset:2112
	buffer_inv sc1
	s_lshl_b32 s23, s21, 5

.Llb_after_12:
.LBB0_1866:
	s_cmp_lt_i32 s78, 16
	s_cselect_b64 s[0:1], -1, 0
	s_and_b64 s[4:5], s[0:1], s[4:5]
	s_andn2_b64 vcc, exec, s[4:5]
	s_cbranch_vccnz .LBB0_1911
	s_cmpk_lt_i32 s2, 0x100
	s_cselect_b64 s[4:5], -1, 0
	s_cmpk_gt_i32 s2, 0xff
	v_readfirstlane_b32 s8, v185
	s_cbranch_scc1 .LBB0_1873
	s_ashr_i32 s3, s2, 31
	s_lshr_b32 s3, s3, 29
	s_add_i32 s3, s2, s3
	s_and_b32 s6, s3, -8
	s_sub_i32 s9, s2, s6
	s_cmp_gt_i32 s9, -1
	s_cbranch_scc0 .LBB0_1870
	s_lshl_b32 s10, s9, 5
	s_cbranch_execz .LBB0_1871
	s_branch .LBB0_1872

.LBB0_1911:
	s_cmp_gt_i32 s79, 16
	s_cselect_b64 s[4:5], -1, 0
	s_and_b64 s[0:1], s[0:1], s[4:5]
	s_andn2_b64 vcc, exec, s[0:1]
	s_cbranch_vccnz .LBB0_1965
	s_waitcnt vmcnt(0) lgkmcnt(0)
	s_barrier
	v_readlane_b32 s12, v243, 0
	s_cmp_eq_u32 s12, 0
	s_cbranch_scc1 .Lfb_13
	v_readlane_b32 s21, v243, 1
	s_add_u32 s21, s21, 1
	v_writelane_b32 v243, s21, 1
	v_readlane_b32 s12, v242, 1
	v_readlane_b32 s13, v242, 2
	s_mov_b64 s[14:15], exec
	s_and_b64 s[12:13], s[14:15], s[12:13]
	s_mov_b64 exec, s[12:13]
	s_cbranch_execz .Llb_done_13
	s_and_b32 s16, s2, 7
	s_lshl_b32 s16, s16, 6
	s_add_u32 s16, s76, s16
	s_addc_u32 s17, s77, 0
	v_mov_b32_e32 v1, 0x3000
	v_mov_b32_e32 v4, 1
	global_atomic_add v1, v4, s[16:17] offset:2112
	buffer_inv sc1
	s_lshl_b32 s23, s21, 5

.Llb_after_13:
.LBB0_1965:
	s_cmp_lt_i32 s78, 17
	s_cselect_b64 s[0:1], -1, 0
	s_and_b64 s[4:5], s[0:1], s[4:5]
	s_andn2_b64 vcc, exec, s[4:5]
	s_cbranch_vccnz .LBB0_1982
	s_cmpk_gt_i32 s2, 0x57f
	v_readfirstlane_b32 s5, v185
	s_cbranch_scc1 .LBB0_1982
	v_lshrrev_b32_e32 v0, 5, v185
	v_lshrrev_b32_e32 v2, 1, v185
	v_and_b32_e32 v0, 4, v0
	s_waitcnt lgkmcnt(0)
	v_bfe_u32 v1, v185, 2, 2
	v_and_b32_e32 v11, 24, v2
	v_or3_b32 v0, v0, v1, v11
	v_lshlrev_b32_e32 v1, 4, v185
	v_add_u32_e32 v8, 0x2000, v1
	v_lshrrev_b32_e32 v2, 7, v8
	s_movk_i32 s4, 0xe0
	v_and_b32_e32 v4, 32, v185
	v_and_or_b32 v3, v2, s4, v0
	v_bitop3_b32 v9, v1, v4, 48 bitop3:0x6c
	v_and_b32_e32 v10, 64, v185
	v_bfe_u32 v12, v185, 2, 4
	s_movk_i32 s4, 0xf0
	v_or_b32_e32 v1, v9, v10
	v_and_or_b32 v2, v2, s4, v12
	s_add_u32 s3, s76, 0x400000
	v_lshl_or_b32 v130, v2, 11, v1
	v_lshrrev_b32_e32 v2, 3, v185
	s_movk_i32 s4, 0x60
	s_addc_u32 s30, s77, 0
	v_and_or_b32 v0, v2, s4, v0
	s_movk_i32 s4, 0x70
	s_ashr_i32 s33, s2, 31
	v_lshl_or_b32 v132, v0, 11, v1
	v_and_or_b32 v0, v2, s4, v12
	s_lshr_b32 s4, s33, 29
	s_add_i32 s4, s2, s4
	s_lshr_b32 s10, s5, 6
	s_ashr_i32 s6, s4, 3
	s_and_b32 s4, s4, -8
	s_lshr_b32 s12, s5, 8
	s_lshl_b32 s31, s10, 10
	s_sub_i32 s4, s2, s4
	s_cmp_lt_i32 s4, 0
	s_movk_i32 s34, 0xb1
	s_cselect_b32 s7, s34, 0xb0
	s_mul_i32 s4, s4, s7
	s_add_i32 s4, s4, s6
	s_mul_hi_i32 s6, s4, 0x2e8ba2e9
	s_lshr_b32 s7, s6, 31
	s_ashr_i32 s6, s6, 4
	s_add_i32 s6, s6, s7
	s_lshl_b32 s7, s6, 2
	s_mulk_i32 s6, 0x58
	s_sub_i32 s6, s4, s6
	s_bfe_i32 s4, s6, 0x80000
	s_bfe_u32 s4, s4, 0x2000d
	s_add_i32 s8, s6, s4
	s_bfe_i32 s4, s8, 0x80000
	s_and_b32 s8, s8, 0xfc
	s_sub_i32 s6, s6, s8
	s_sext_i32_i16 s4, s4
	s_sext_i32_i8 s6, s6
	s_lshr_b32 s4, s4, 2
	s_add_i32 s22, s7, s6
	s_ashr_i32 s23, s22, 31
	s_bfe_i64 s[8:9], s[4:5], 0x100000
	s_lshl_b64 s[6:7], s[22:23], 19
	s_lshl_b64 s[8:9], s[8:9], 19
	s_add_u32 s26, s3, s8
	s_addc_u32 s27, s30, s9
	s_add_i32 s23, s31, 0
	s_add_i32 m0, s23, 0x10000
	v_lshl_or_b32 v128, v3, 11, v1
	global_load_lds_dwordx4 v132, s[26:27]
	s_add_i32 m0, s23, 0x12000
	s_add_u32 s8, s26, 0x40000
	global_load_lds_dwordx4 v128, s[26:27]
	s_addc_u32 s9, s27, 0
	s_add_i32 m0, s23, 0x14000
	v_lshl_or_b32 v134, v0, 11, v1
	global_load_lds_dwordx4 v132, s[8:9]
	s_add_i32 m0, s23, 0x16000
	s_add_u32 s24, s82, s6
	s_addc_u32 s25, s83, s7
	s_add_i32 s35, s23, 0x2000
	global_load_lds_dwordx4 v128, s[8:9]
	s_mov_b32 m0, s23
	s_add_u32 s6, s24, 0x40000
	global_load_lds_dwordx4 v134, s[24:25]
	s_mov_b32 m0, s35
	s_addc_u32 s7, s25, 0
	s_add_i32 s36, s23, 0x4000
	global_load_lds_dwordx4 v130, s[24:25]
	s_mov_b32 m0, s36
	s_add_i32 s37, s23, 0x6000
	global_load_lds_dwordx4 v134, s[6:7]
	s_mov_b32 m0, s37
	v_mov_b32_e32 v133, 0
	global_load_lds_dwordx4 v130, s[6:7]
	v_mov_b32_e32 v129, v133
	v_mov_b32_e32 v135, v133
	v_mov_b32_e32 v131, v133
	s_cmp_eq_u32 s12, 1
	s_mov_b32 s38, 0
	v_lshl_add_u64 v[6:7], s[26:27], 0, v[132:133]
	v_lshl_add_u64 v[4:5], s[26:27], 0, v[128:129]
	v_lshl_add_u64 v[0:1], s[24:25], 0, v[134:135]
	s_cselect_b64 s[6:7], -1, 0
	s_cmp_lg_u32 s12, 1
	v_lshl_add_u64 v[2:3], s[24:25], 0, v[130:131]
	s_cbranch_scc1 .LBB0_1969
	s_barrier

.LBB0_1982:
	s_cmp_gt_i32 s79, 17
	s_cselect_b64 s[4:5], -1, 0
	s_and_b64 s[0:1], s[0:1], s[4:5]
	s_andn2_b64 vcc, exec, s[0:1]
	s_cbranch_vccnz .LBB0_2036
	s_waitcnt vmcnt(0) lgkmcnt(0)
	s_barrier
	v_readlane_b32 s12, v243, 0
	s_cmp_eq_u32 s12, 0
	s_cbranch_scc1 .Lfb_14
	v_readlane_b32 s21, v243, 1
	s_add_u32 s21, s21, 1
	v_writelane_b32 v243, s21, 1
	v_readlane_b32 s12, v242, 1
	v_readlane_b32 s13, v242, 2
	s_mov_b64 s[14:15], exec
	s_and_b64 s[12:13], s[14:15], s[12:13]
	s_mov_b64 exec, s[12:13]
	s_cbranch_execz .Llb_done_14
	s_and_b32 s16, s2, 7
	s_lshl_b32 s16, s16, 6
	s_add_u32 s16, s76, s16
	s_addc_u32 s17, s77, 0
	v_mov_b32_e32 v1, 0x3000
	v_mov_b32_e32 v4, 1
	global_atomic_add v1, v4, s[16:17] offset:2112
	buffer_inv sc1
	s_lshl_b32 s23, s21, 5

.Llb_after_14:
.LBB0_2036:
	s_cmp_lt_i32 s78, 18
	s_cselect_b64 s[6:7], -1, 0
	s_and_b64 s[0:1], s[6:7], s[4:5]
	s_andn2_b64 vcc, exec, s[0:1]
	s_cbranch_vccnz .LBB0_2065
	s_cmpk_gt_i32 s2, 0xff
	v_readfirstlane_b32 s4, v185
	s_cbranch_scc1 .LBB0_2065
	s_ashr_i32 s3, s2, 31
	s_lshr_b32 s0, s3, 29
	s_add_i32 s9, s2, s0
	s_and_b32 s0, s9, -8
	s_sub_i32 s5, s2, s0
	s_cmp_gt_i32 s5, -1
	s_cbranch_scc0 .LBB0_2040
	s_lshl_b32 s8, s5, 5
	s_ashr_i32 s1, s9, 3
	s_cbranch_execz .LBB0_2041
	s_branch .LBB0_2042

	.amdhsa_kernel _Z10fwd_kernel4Args
		.amdhsa_group_segment_fixed_size 0
		.amdhsa_private_segment_fixed_size 0
		.amdhsa_kernarg_size 464
		.amdhsa_user_sgpr_count 2
		.amdhsa_user_sgpr_dispatch_ptr 0
		.amdhsa_user_sgpr_queue_ptr 0
		.amdhsa_user_sgpr_kernarg_segment_ptr 1
		.amdhsa_user_sgpr_dispatch_id 0
		.amdhsa_user_sgpr_kernarg_preload_length 0
		.amdhsa_user_sgpr_kernarg_preload_offset 0
		.amdhsa_user_sgpr_private_segment_size 0
		.amdhsa_uses_dynamic_stack 0
		.amdhsa_enable_private_segment 0
		.amdhsa_system_sgpr_workgroup_id_x 1
		.amdhsa_system_sgpr_workgroup_id_y 0
		.amdhsa_system_sgpr_workgroup_id_z 0
		.amdhsa_system_sgpr_workgroup_info 0
		.amdhsa_system_vgpr_workitem_id 2
		.amdhsa_next_free_vgpr 244
		.amdhsa_next_free_sgpr 102
		.amdhsa_accum_offset 244
		.amdhsa_reserve_vcc 1
		.amdhsa_float_round_mode_32 0
		.amdhsa_float_round_mode_16_64 0
		.amdhsa_float_denorm_mode_32 3
		.amdhsa_float_denorm_mode_16_64 3
		.amdhsa_dx10_clamp 1
		.amdhsa_ieee_mode 1
		.amdhsa_fp16_overflow 0
		.amdhsa_tg_split 0
		.amdhsa_exception_fp_ieee_invalid_op 0
		.amdhsa_exception_fp_denorm_src 0
		.amdhsa_exception_fp_ieee_div_zero 0
		.amdhsa_exception_fp_ieee_overflow 0
		.amdhsa_exception_fp_ieee_underflow 0
		.amdhsa_exception_fp_ieee_inexact 0
		.amdhsa_exception_int_div_zero 0
	.end_amdhsa_kernel

amdhsa.kernels:
  - .agpr_count:     0
    .args:
      - .offset:         0
        .size:           208
        .value_kind:     by_value
      - .offset:         208
        .size:           4
        .value_kind:     hidden_block_count_x
      - .offset:         212
        .size:           4
        .value_kind:     hidden_block_count_y
      - .offset:         216
        .size:           4
        .value_kind:     hidden_block_count_z
      - .offset:         220
        .size:           2
        .value_kind:     hidden_group_size_x
      - .offset:         222
        .size:           2
        .value_kind:     hidden_group_size_y
      - .offset:         224
        .size:           2
        .value_kind:     hidden_group_size_z
      - .offset:         226
        .size:           2
        .value_kind:     hidden_remainder_x
      - .offset:         228
        .size:           2
        .value_kind:     hidden_remainder_y
      - .offset:         230
        .size:           2
        .value_kind:     hidden_remainder_z
      - .offset:         248
        .size:           8
        .value_kind:     hidden_global_offset_x
      - .offset:         256
        .size:           8
        .value_kind:     hidden_global_offset_y
      - .offset:         264
        .size:           8
        .value_kind:     hidden_global_offset_z
      - .offset:         272
        .size:           2
        .value_kind:     hidden_grid_dims
      - .offset:         296
        .size:           8
        .value_kind:     hidden_multigrid_sync_arg
      - .offset:         328
        .size:           4
        .value_kind:     hidden_dynamic_lds_size
    .group_segment_fixed_size: 0
    .kernarg_segment_align: 8
    .kernarg_segment_size: 464
    .language:       OpenCL C
    .language_version:
      - 2
      - 0
    .max_flat_workgroup_size: 512
    .name:           _Z10fwd_kernel4Args
    .private_segment_fixed_size: 0
    .sgpr_count:     108
    .sgpr_spill_count: 64
    .symbol:         _Z10fwd_kernel4Args.kd
    .uniform_work_group_size: 1
    .uses_dynamic_stack: false
    .vgpr_count:     244
    .vgpr_spill_count: 0
    .wavefront_size: 64
